# mem_attn output stores: 32 two-byte stores per lane become 16 dword stores (even lanes tile t, odd lanes tile t+1, neighbour column via DPP quad_perm)
# baseline (speedup 1.0000x reference)
; #define LAS __attribute__((address_space(3)))
; DI int lbid() { int b = (int)blockIdx.x; asm volatile("" : "+s"(b)); return b; }
; DI int lgdim() { int g = (int)gridDim.x; asm volatile("" : "+s"(g)); return g; }
; DI f32x4 mfma16(bf16x8 a, bf16x8 b, f32x4 c) { return __builtin_amdgcn_mfma_f32_16x16x32_bf16(a, b, c, 0, 0, 0); }
; DI void mem_attn_phase(const Params& P, LAS unsigned char* lds, int r, int layer, const bf16* QKV, int nin, int qoff, bf16* CAT) {
;     ...
;     for (int u = lbid(); u < 512; u += lgdim()) {
;         int g = g0, li = li0; asm volatile("" : "+v"(g), "+v"(li));
;         const int h = u & 3, qt = u >> 2;
;         const int s = (qt * 128) / L;
;         const bf16* kb = MEMKV + (size_t)(memrow0 + s * 256) * 1024 + h * 128;
;         { v4u kreg[8], vreg[8];
;         _Pragma("unroll") for (int it_ = 0; it_ < 8; ++it_) { const int task = tid + 512 * it_; const int m = task >> 4, c = task & 15;
;             kreg[it_] = *(const v4u*)(kb + (size_t)m * 1024 + c * 8); vreg[it_] = *(const v4u*)(kb + (size_t)m * 1024 + 512 + c * 8); }
;         asm volatile("" ::: "memory");
;         _Pragma("unroll") for (int it_ = 0; it_ < 8; ++it_) { const int task = tid + 512 * it_; const int m = task >> 4, c = task & 15;
;             *(LAS v4u*)(KI + m * PITCH + c * 16) = kreg[it_]; *(LAS v4u*)(VI + m * PITCH + c * 16) = vreg[it_]; } }
;         __syncthreads();
;         const int row0 = qt * 128 + wave * 16;
;         const bf16* qp = QKV + (size_t)(row0 + li) * nin + qoff + h * 128 + 8 * g;
;         bf16x8 qa[4];
; #pragma unroll
;         for (int ks = 0; ks < 4; ++ks) qa[ks] = __builtin_nontemporal_load((const bf16x8*)(qp + 32 * ks));
;         f32x4 sacc[16];
; #pragma unroll
;         for (int t = 0; t < 16; ++t) sacc[t] = (f32x4){0.f, 0.f, 0.f, 0.f};
; #pragma unroll
;         for (int tb = 0; tb < 4; ++tb)
; #pragma unroll
;             for (int ks = 0; ks < 4; ++ks) { bf16x8 kf[4];
; #pragma unroll
;                 for (int t = 0; t < 4; ++t) kf[t] = frag_row(KI, PITCH, 16 * (4 * tb + t), 32 * ks, lane);
;                 __builtin_amdgcn_sched_barrier(0);
; #pragma unroll
;                 for (int t = 0; t < 4; ++t) sacc[4 * tb + t] = mfma16(qa[ks], kf[t], sacc[4 * tb + t]);
.LBB0_220:
	s_lshl_b32 s9, s0, 5
	s_and_b32 s9, s9, 0xffffff80
	s_bfe_i32 s10, s0, 0x1001a
	s_add_i32 s11, s9, s10
	s_xor_b32 s11, s11, s10
	s_mul_hi_u32 s12, s11, s8
	s_mul_i32 s13, s12, s82
	s_sub_i32 s11, s11, s13
	s_add_i32 s13, s12, 1
	s_sub_i32 s14, s11, s82
	s_cmp_ge_u32 s11, s82
	s_cselect_b32 s12, s13, s12
	s_cselect_b32 s11, s14, s11
	s_add_i32 s13, s12, 1
	s_cmp_ge_u32 s11, s82
	s_cselect_b32 s11, s13, s12
	s_xor_b32 s11, s11, s10
	s_sub_i32 s10, s11, s10
	s_lshl_b32 s10, s10, 8
	s_add_i32 s10, s10, s3
	s_ashr_i32 s11, s10, 31
	s_lshl_b64 s[10:11], s[10:11], 11
	s_add_u32 s10, s1, s10
	s_addc_u32 s11, s2, s11
	s_lshl_b32 s12, s0, 8
	s_and_b32 s62, s12, 0x300
	s_add_u32 s10, s10, s62
	s_addc_u32 s11, s11, 0
	v_lshl_add_u64 v[0:1], s[10:11], 0, v[64:65]
	v_lshl_add_u64 v[8:9], s[10:11], 0, v[66:67]
	v_lshl_add_u64 v[16:17], s[10:11], 0, v[68:69]
	v_lshl_add_u64 v[24:25], s[10:11], 0, v[70:71]
	v_lshl_add_u64 v[32:33], s[10:11], 0, v[72:73]
	v_lshl_add_u64 v[40:41], s[10:11], 0, v[74:75]
	v_lshl_add_u64 v[48:49], s[10:11], 0, v[76:77]
	v_lshl_add_u64 v[56:57], s[10:11], 0, v[78:79]
	v_mov_b32_e32 v81, v82
	v_mov_b32_e32 v80, v83
	v_lshl_add_u64 v[4:5], v[0:1], 0, v[128:129]
	v_lshl_add_u64 v[12:13], v[8:9], 0, v[128:129]
	v_lshl_add_u64 v[20:21], v[16:17], 0, v[128:129]
	v_lshl_add_u64 v[28:29], v[24:25], 0, v[128:129]
	v_lshl_add_u64 v[36:37], v[32:33], 0, v[128:129]
	v_lshl_add_u64 v[44:45], v[40:41], 0, v[128:129]
	v_lshl_add_u64 v[52:53], v[48:49], 0, v[128:129]
	v_lshl_add_u64 v[60:61], v[56:57], 0, v[128:129]
	flat_load_dwordx4 v[0:3], v[4:5]
	s_nop 0
	flat_load_dwordx4 v[4:7], v[4:5] offset:1024
	s_nop 0
	flat_load_dwordx4 v[8:11], v[12:13]
	s_nop 0
	flat_load_dwordx4 v[12:15], v[12:13] offset:1024
	s_nop 0
	flat_load_dwordx4 v[16:19], v[20:21]
	s_nop 0
	flat_load_dwordx4 v[20:23], v[20:21] offset:1024
	s_nop 0
	flat_load_dwordx4 v[24:27], v[28:29]
	s_nop 0
	flat_load_dwordx4 v[28:31], v[28:29] offset:1024
	s_nop 0
	flat_load_dwordx4 v[32:35], v[36:37]
	s_nop 0
	flat_load_dwordx4 v[36:39], v[36:37] offset:1024
	s_nop 0
	flat_load_dwordx4 v[40:43], v[44:45]
	s_nop 0
	flat_load_dwordx4 v[44:47], v[44:45] offset:1024
	s_nop 0
	flat_load_dwordx4 v[48:51], v[52:53]
	s_nop 0
	flat_load_dwordx4 v[52:55], v[52:53] offset:1024
	s_nop 0
	flat_load_dwordx4 v[56:59], v[60:61]
	s_nop 0
	flat_load_dwordx4 v[60:63], v[60:61] offset:1024
	s_add_i32 s9, s9, s7
	v_add_u32_e32 v100, s9, v80
	v_mad_i64_i32 v[100:101], s[10:11], s6, v100, 0
	v_lshlrev_b32_e32 v98, 3, v81
	v_lshl_add_u64 v[100:101], v[100:101], 1, s[4:5]
	v_add_u32_e32 v97, v84, v86
	v_ashrrev_i32_e32 v99, 31, v98
	v_lshl_add_u64 v[100:101], v[100:101], 0, s[62:63]
	v_add_u32_e32 v102, v85, v86
	v_add_u32_e32 v103, v84, v87
	v_add_u32_e32 v104, v85, v87
	v_add_u32_e32 v105, v84, v88
	v_add_u32_e32 v106, v85, v88
	v_add_u32_e32 v107, v84, v89
	v_add_u32_e32 v108, v85, v89
	v_add_u32_e32 v109, v84, v90
	v_add_u32_e32 v110, v85, v90
	v_add_u32_e32 v111, v84, v91
	v_add_u32_e32 v112, v85, v91
	v_add_u32_e32 v113, v84, v92
	v_add_u32_e32 v114, v85, v92
	v_add_u32_e32 v115, v84, v93
	v_add_u32_e32 v116, v85, v93
	s_waitcnt vmcnt(0) lgkmcnt(0)
	ds_write_b128 v97, v[0:3]
	ds_write_b128 v102, v[4:7]
	ds_write_b128 v103, v[8:11]
	ds_write_b128 v104, v[12:15]
	ds_write_b128 v105, v[16:19]
	ds_write_b128 v106, v[20:23]
	ds_write_b128 v107, v[24:27]
	ds_write_b128 v108, v[28:31]
	ds_write_b128 v109, v[32:35]
	ds_write_b128 v110, v[36:39]
	ds_write_b128 v111, v[40:43]
	ds_write_b128 v112, v[44:47]
	ds_write_b128 v113, v[48:51]
	ds_write_b128 v114, v[52:55]
	ds_write_b128 v115, v[56:59]
	ds_write_b128 v116, v[60:63]
	v_lshl_add_u64 v[0:1], v[98:99], 1, v[100:101]
	s_waitcnt lgkmcnt(0)
	s_barrier
	flat_load_dwordx4 v[20:23], v[0:1] nt
	flat_load_dwordx4 v[36:39], v[0:1] offset:64 nt
	flat_load_dwordx4 v[52:55], v[0:1] offset:128 nt
	flat_load_dwordx4 v[98:101], v[0:1] offset:192 nt
	ds_read_b128 v[0:3], v94
	ds_read_b128 v[4:7], v94 offset:4352
	ds_read_b128 v[8:11], v94 offset:8704
	ds_read_b128 v[12:15], v94 offset:13056
	s_waitcnt vmcnt(0) lgkmcnt(0)
	v_mfma_f32_16x16x32_bf16 v[0:3], v[20:23], v[0:3], 0
	v_mfma_f32_16x16x32_bf16 v[4:7], v[20:23], v[4:7], 0
	v_mfma_f32_16x16x32_bf16 v[8:11], v[20:23], v[8:11], 0
	v_mfma_f32_16x16x32_bf16 v[12:15], v[20:23], v[12:15], 0
	ds_read_b128 v[16:19], v94 offset:64
	ds_read_b128 v[24:27], v94 offset:4416
	ds_read_b128 v[28:31], v94 offset:8768
	ds_read_b128 v[32:35], v94 offset:13120
	s_waitcnt lgkmcnt(3)
	v_mfma_f32_16x16x32_bf16 v[0:3], v[36:39], v[16:19], v[0:3]
	s_waitcnt lgkmcnt(2)
	v_mfma_f32_16x16x32_bf16 v[4:7], v[36:39], v[24:27], v[4:7]
	s_waitcnt lgkmcnt(1)
	v_mfma_f32_16x16x32_bf16 v[8:11], v[36:39], v[28:31], v[8:11]
	s_waitcnt lgkmcnt(0)
	v_mfma_f32_16x16x32_bf16 v[12:15], v[36:39], v[32:35], v[12:15]
	ds_read_b128 v[16:19], v94 offset:128
	ds_read_b128 v[24:27], v94 offset:4480
	ds_read_b128 v[28:31], v94 offset:8832
	ds_read_b128 v[32:35], v94 offset:13184
	s_waitcnt lgkmcnt(3)
	v_mfma_f32_16x16x32_bf16 v[0:3], v[52:55], v[16:19], v[0:3]
	s_waitcnt lgkmcnt(2)
	v_mfma_f32_16x16x32_bf16 v[4:7], v[52:55], v[24:27], v[4:7]
	s_waitcnt lgkmcnt(1)
	v_mfma_f32_16x16x32_bf16 v[8:11], v[52:55], v[28:31], v[8:11]
	s_waitcnt lgkmcnt(0)
	v_mfma_f32_16x16x32_bf16 v[12:15], v[52:55], v[32:35], v[12:15]
	ds_read_b128 v[16:19], v94 offset:192
	ds_read_b128 v[24:27], v94 offset:4544
	ds_read_b128 v[28:31], v94 offset:8896
	ds_read_b128 v[32:35], v94 offset:13248
	s_waitcnt lgkmcnt(3)
	v_mfma_f32_16x16x32_bf16 v[40:43], v[98:101], v[16:19], v[0:3]
	s_waitcnt lgkmcnt(2)
	v_mfma_f32_16x16x32_bf16 v[24:27], v[98:101], v[24:27], v[4:7]
	s_waitcnt lgkmcnt(1)
; DI f32x4 mfma16(bf16x8 a, bf16x8 b, f32x4 c) { return __builtin_amdgcn_mfma_f32_16x16x32_bf16(a, b, c, 0, 0, 0); }
; DI void mem_attn_phase(const Params& P, LAS unsigned char* lds, int r, int layer, const bf16* QKV, int nin, int qoff, bf16* CAT) {
;     ...
;         for (int tb = 0; tb < 4; ++tb)
; #pragma unroll
;             for (int ks = 0; ks < 4; ++ks) { bf16x8 kf[4];
; #pragma unroll
;                 for (int t = 0; t < 4; ++t) kf[t] = frag_row(KI, PITCH, 16 * (4 * tb + t), 32 * ks, lane);
;                 __builtin_amdgcn_sched_barrier(0);
; #pragma unroll
;                 for (int t = 0; t < 4; ++t) sacc[4 * tb + t] = mfma16(qa[ks], kf[t], sacc[4 * tb + t]);
;                 __builtin_amdgcn_sched_barrier(0); }
	v_mfma_f32_16x16x32_bf16 v[8:11], v[98:101], v[28:31], v[8:11]
	s_waitcnt lgkmcnt(0)
	v_mfma_f32_16x16x32_bf16 v[0:3], v[98:101], v[32:35], v[12:15]
	ds_read_b128 v[4:7], v94 offset:17408
	s_nop 1
	ds_read_b128 v[12:15], v94 offset:21760
	ds_read_b128 v[16:19], v94 offset:26112
	ds_read_b128 v[28:31], v94 offset:30464
	s_waitcnt lgkmcnt(3)
	v_mfma_f32_16x16x32_bf16 v[4:7], v[20:23], v[4:7], 0
	s_waitcnt lgkmcnt(2)
	v_mfma_f32_16x16x32_bf16 v[12:15], v[20:23], v[12:15], 0
	s_waitcnt lgkmcnt(1)
	v_mfma_f32_16x16x32_bf16 v[16:19], v[20:23], v[16:19], 0
	s_waitcnt lgkmcnt(0)
	v_mfma_f32_16x16x32_bf16 v[28:31], v[20:23], v[28:31], 0
	ds_read_b128 v[32:35], v94 offset:17472
	ds_read_b128 v[44:47], v94 offset:21824
	ds_read_b128 v[48:51], v94 offset:26176
	ds_read_b128 v[56:59], v94 offset:30528
	s_waitcnt lgkmcnt(3)
	v_mfma_f32_16x16x32_bf16 v[4:7], v[36:39], v[32:35], v[4:7]
	s_waitcnt lgkmcnt(2)
	v_mfma_f32_16x16x32_bf16 v[12:15], v[36:39], v[44:47], v[12:15]
	s_waitcnt lgkmcnt(1)
	v_mfma_f32_16x16x32_bf16 v[16:19], v[36:39], v[48:51], v[16:19]
	s_waitcnt lgkmcnt(0)
	v_mfma_f32_16x16x32_bf16 v[28:31], v[36:39], v[56:59], v[28:31]
	ds_read_b128 v[32:35], v94 offset:17536
	ds_read_b128 v[44:47], v94 offset:21888
	ds_read_b128 v[48:51], v94 offset:26240
	ds_read_b128 v[56:59], v94 offset:30592
	s_waitcnt lgkmcnt(3)
	v_mfma_f32_16x16x32_bf16 v[4:7], v[52:55], v[32:35], v[4:7]
	s_waitcnt lgkmcnt(2)
	v_mfma_f32_16x16x32_bf16 v[12:15], v[52:55], v[44:47], v[12:15]
	s_waitcnt lgkmcnt(1)
	v_mfma_f32_16x16x32_bf16 v[16:19], v[52:55], v[48:51], v[16:19]
	s_waitcnt lgkmcnt(0)
	v_mfma_f32_16x16x32_bf16 v[28:31], v[52:55], v[56:59], v[28:31]
	ds_read_b128 v[32:35], v94 offset:17600
	ds_read_b128 v[44:47], v94 offset:21952
	ds_read_b128 v[56:59], v94 offset:26304
	ds_read_b128 v[60:63], v94 offset:30656
	s_waitcnt lgkmcnt(3)
	v_mfma_f32_16x16x32_bf16 v[48:51], v[98:101], v[32:35], v[4:7]
	s_waitcnt lgkmcnt(2)
	v_mfma_f32_16x16x32_bf16 v[32:35], v[98:101], v[44:47], v[12:15]
	s_waitcnt lgkmcnt(1)
	v_mfma_f32_16x16x32_bf16 v[16:19], v[98:101], v[56:59], v[16:19]
	s_waitcnt lgkmcnt(0)
	v_mfma_f32_16x16x32_bf16 v[4:7], v[98:101], v[60:63], v[28:31]
	ds_read_b128 v[12:15], v94 offset:34816
	s_nop 1
	ds_read_b128 v[28:31], v94 offset:39168
	ds_read_b128 v[44:47], v94 offset:43520
	ds_read_b128 v[56:59], v94 offset:47872
	s_waitcnt lgkmcnt(3)
	v_mfma_f32_16x16x32_bf16 v[12:15], v[20:23], v[12:15], 0
	s_waitcnt lgkmcnt(2)
	v_mfma_f32_16x16x32_bf16 v[28:31], v[20:23], v[28:31], 0
	s_waitcnt lgkmcnt(1)
	v_mfma_f32_16x16x32_bf16 v[44:47], v[20:23], v[44:47], 0
	s_waitcnt lgkmcnt(0)
	v_mfma_f32_16x16x32_bf16 v[56:59], v[20:23], v[56:59], 0
	ds_read_b128 v[60:63], v94 offset:34880
	ds_read_b128 v[102:105], v94 offset:39232
	ds_read_b128 v[106:109], v94 offset:43584
	ds_read_b128 v[110:113], v94 offset:47936
	s_waitcnt lgkmcnt(3)
	v_mfma_f32_16x16x32_bf16 v[12:15], v[36:39], v[60:63], v[12:15]
	s_waitcnt lgkmcnt(2)
	v_mfma_f32_16x16x32_bf16 v[28:31], v[36:39], v[102:105], v[28:31]
	s_waitcnt lgkmcnt(1)
	v_mfma_f32_16x16x32_bf16 v[44:47], v[36:39], v[106:109], v[44:47]
	s_waitcnt lgkmcnt(0)
	v_mfma_f32_16x16x32_bf16 v[56:59], v[36:39], v[110:113], v[56:59]
	ds_read_b128 v[60:63], v94 offset:34944
	ds_read_b128 v[102:105], v94 offset:39296
	ds_read_b128 v[106:109], v94 offset:43648
	ds_read_b128 v[110:113], v94 offset:48000
	s_waitcnt lgkmcnt(3)
	v_mfma_f32_16x16x32_bf16 v[12:15], v[52:55], v[60:63], v[12:15]
	s_waitcnt lgkmcnt(2)
	v_mfma_f32_16x16x32_bf16 v[28:31], v[52:55], v[102:105], v[28:31]
	s_waitcnt lgkmcnt(1)
	v_mfma_f32_16x16x32_bf16 v[60:63], v[52:55], v[106:109], v[44:47]
	s_waitcnt lgkmcnt(0)
	v_mfma_f32_16x16x32_bf16 v[102:105], v[52:55], v[110:113], v[56:59]
	s_nop 0
	ds_read_b128 v[44:47], v94 offset:35008
	ds_read_b128 v[106:109], v94 offset:39360
	ds_read_b128 v[110:113], v94 offset:43712
	ds_read_b128 v[114:117], v94 offset:48064
	s_waitcnt lgkmcnt(3)
	v_mfma_f32_16x16x32_bf16 v[56:59], v[98:101], v[44:47], v[12:15]
	s_waitcnt lgkmcnt(2)
	v_mfma_f32_16x16x32_bf16 v[44:47], v[98:101], v[106:109], v[28:31]
	s_waitcnt lgkmcnt(1)
	v_mfma_f32_16x16x32_bf16 v[28:31], v[98:101], v[110:113], v[60:63]
	s_waitcnt lgkmcnt(0)
	v_mfma_f32_16x16x32_bf16 v[12:15], v[98:101], v[114:117], v[102:105]
	s_nop 0
	ds_read_b128 v[60:63], v94 offset:52224
	s_nop 0
	ds_read_b128 v[102:105], v94 offset:56576
	ds_read_b128 v[106:109], v94 offset:60928
	ds_read_b128 v[110:113], v94 offset:65280
	s_waitcnt lgkmcnt(3)
	v_mfma_f32_16x16x32_bf16 v[60:63], v[20:23], v[60:63], 0
	s_waitcnt lgkmcnt(2)
	v_mfma_f32_16x16x32_bf16 v[102:105], v[20:23], v[102:105], 0
	s_waitcnt lgkmcnt(1)
	v_mfma_f32_16x16x32_bf16 v[106:109], v[20:23], v[106:109], 0
	s_waitcnt lgkmcnt(0)
	v_mfma_f32_16x16x32_bf16 v[20:23], v[20:23], v[110:113], 0
	ds_read_b128 v[110:113], v94 offset:52288
	ds_read_b128 v[114:117], v94 offset:56640
	ds_read_b128 v[118:121], v94 offset:60992
	ds_read_b128 v[122:125], v94 offset:65344
	s_waitcnt lgkmcnt(3)
	v_mfma_f32_16x16x32_bf16 v[60:63], v[36:39], v[110:113], v[60:63]
	s_waitcnt lgkmcnt(2)
	v_mfma_f32_16x16x32_bf16 v[102:105], v[36:39], v[114:117], v[102:105]
	s_waitcnt lgkmcnt(1)
	v_mfma_f32_16x16x32_bf16 v[106:109], v[36:39], v[118:121], v[106:109]
	s_waitcnt lgkmcnt(0)
	v_mfma_f32_16x16x32_bf16 v[20:23], v[36:39], v[122:125], v[20:23]
	ds_read_b128 v[36:39], v94 offset:52352
	ds_read_b128 v[110:113], v94 offset:56704
	ds_read_b128 v[114:117], v94 offset:61056
	ds_read_b128 v[118:121], v94 offset:65408
	s_waitcnt lgkmcnt(3)
	v_mfma_f32_16x16x32_bf16 v[36:39], v[52:55], v[36:39], v[60:63]
	s_waitcnt lgkmcnt(2)
	v_mfma_f32_16x16x32_bf16 v[102:105], v[52:55], v[110:113], v[102:105]
	s_waitcnt lgkmcnt(1)
	v_mfma_f32_16x16x32_bf16 v[106:109], v[52:55], v[114:117], v[106:109]
	s_waitcnt lgkmcnt(0)
	v_mfma_f32_16x16x32_bf16 v[20:23], v[52:55], v[118:121], v[20:23]
	ds_read_b128 v[52:55], v94 offset:52416
	ds_read_b128 v[110:113], v94 offset:56768
	ds_read_b128 v[114:117], v94 offset:61120
	ds_read_b128 v[118:121], v94 offset:65472
	s_waitcnt lgkmcnt(3)
	v_mfma_f32_16x16x32_bf16 v[60:63], v[98:101], v[52:55], v[36:39]
	s_waitcnt lgkmcnt(2)
	v_mfma_f32_16x16x32_bf16 v[52:55], v[98:101], v[110:113], v[102:105]
	s_waitcnt lgkmcnt(1)
	v_mfma_f32_16x16x32_bf16 v[36:39], v[98:101], v[114:117], v[106:109]
	s_waitcnt lgkmcnt(0)
	v_mfma_f32_16x16x32_bf16 v[20:23], v[98:101], v[118:121], v[20:23]
	v_cmp_lt_i32_e32 vcc, v159, v158
	s_barrier
; DI float fexp2(float x) { return __builtin_amdgcn_exp2f(x); }
; DI float grp16_sum(float v) { v += __shfl_xor(v, 1); v += __shfl_xor(v, 2); v += __shfl_xor(v, 4); v += __shfl_xor(v, 8); return v; }
; DI float grp16_max(float v) { v = fmaxf(v, __shfl_xor(v, 1)); v = fmaxf(v, __shfl_xor(v, 2)); v = fmaxf(v, __shfl_xor(v, 4)); v = fmaxf(v, __shfl_xor(v, 8)); return v; }
; DI void mem_attn_phase(const Params& P, LAS unsigned char* lds, int r, int layer, const bf16* QKV, int nin, int qoff, bf16* CAT) {
;     ...
;         float inv[4];
; #pragma unroll
;         for (int i = 0; i < 4; ++i) { float mx = -INFINITY;
; #pragma unroll
;             for (int t = 0; t < 16; ++t) mx = fmaxf(mx, sacc[t][i]);
;             mx = grp16_max(mx); float sm = 0.f;
; #pragma unroll
;             for (int t = 0; t < 16; ++t) { const float e = fexp2((sacc[t][i] - mx) * (QK_SCALE * LOG2E)); sacc[t][i] = e; sm += e; }
;             inv[i] = 1.0f / grp16_sum(sm); }
	s_nop 0
	v_cndmask_b32_e32 v97, v156, v159, vcc
	v_lshlrev_b32_e32 v101, 2, v97
	v_max3_f32 v97, v40, s86, v24
	v_max3_f32 v97, v97, v8, v0
	v_max3_f32 v97, v97, v48, v32
	v_max3_f32 v97, v97, v16, v4
	v_max3_f32 v97, v97, v56, v44
	v_max3_f32 v97, v97, v28, v12
	v_max3_f32 v97, v97, v60, v52
	v_max3_f32 v97, v97, v36, v20
	ds_bpermute_b32 v98, v101, v97
	v_cmp_lt_i32_e32 vcc, v160, v158
	s_waitcnt lgkmcnt(0)
	v_max_f32_e32 v98, v98, v98
	v_cndmask_b32_e32 v99, v156, v160, vcc
	v_lshlrev_b32_e32 v105, 2, v99
	v_max_f32_e32 v97, v97, v98
	ds_bpermute_b32 v98, v105, v97
	v_cmp_lt_i32_e32 vcc, v161, v158
	s_waitcnt lgkmcnt(0)
	v_max_f32_e32 v98, v98, v98
	v_cndmask_b32_e32 v99, v156, v161, vcc
	v_lshlrev_b32_e32 v106, 2, v99
	v_max_f32_e32 v97, v97, v98
	ds_bpermute_b32 v98, v106, v97
	v_cmp_lt_i32_e32 vcc, v162, v158
	s_waitcnt lgkmcnt(0)
	v_max_f32_e32 v98, v98, v98
	v_cndmask_b32_e32 v99, v156, v162, vcc
	v_lshlrev_b32_e32 v107, 2, v99
	v_max_f32_e32 v97, v97, v98
	ds_bpermute_b32 v98, v107, v97
	s_waitcnt lgkmcnt(0)
	v_max_f32_e32 v98, v98, v98
	v_max_f32_e32 v108, v97, v98
	v_sub_f32_e32 v40, v40, v108
	v_sub_f32_e32 v8, v8, v108
	v_sub_f32_e32 v24, v24, v108
	v_mul_f32_e32 v40, 0x3e0293ee, v40
	v_mul_f32_e32 v8, 0x3e0293ee, v8
	v_mul_f32_e32 v24, 0x3e0293ee, v24
	v_exp_f32_e32 v104, v40
	v_exp_f32_e32 v102, v8
	v_sub_f32_e32 v8, v48, v108
	v_exp_f32_e32 v103, v24
	v_sub_f32_e32 v0, v0, v108
	v_mul_f32_e32 v8, 0x3e0293ee, v8
	v_sub_f32_e32 v4, v4, v108
	v_mul_f32_e32 v0, 0x3e0293ee, v0
	v_exp_f32_e32 v100, v8
	v_sub_f32_e32 v8, v32, v108
	v_mul_f32_e32 v4, 0x3e0293ee, v4
	v_exp_f32_e32 v99, v0
	v_mul_f32_e32 v8, 0x3e0293ee, v8
	v_exp_f32_e32 v40, v4
	v_sub_f32_e32 v4, v56, v108
	v_add_f32_e32 v0, 0, v104
	v_exp_f32_e32 v98, v8
	v_sub_f32_e32 v8, v16, v108
	v_mul_f32_e32 v4, 0x3e0293ee, v4
	v_add_f32_e32 v0, v103, v0
	v_mul_f32_e32 v8, 0x3e0293ee, v8
	v_exp_f32_e32 v48, v4
	v_sub_f32_e32 v4, v44, v108
	v_add_f32_e32 v0, v102, v0
	v_exp_f32_e32 v97, v8
	v_mul_f32_e32 v4, 0x3e0293ee, v4
	v_add_f32_e32 v0, v99, v0
	v_exp_f32_e32 v32, v4
	v_sub_f32_e32 v4, v28, v108
	v_add_f32_e32 v0, v100, v0
	v_mul_f32_e32 v4, 0x3e0293ee, v4
	v_add_f32_e32 v0, v98, v0
	v_exp_f32_e32 v24, v4
	v_sub_f32_e32 v4, v12, v108
	v_add_f32_e32 v0, v97, v0
	v_mul_f32_e32 v4, 0x3e0293ee, v4
	v_add_f32_e32 v0, v40, v0
	v_exp_f32_e32 v12, v4
	v_add_f32_e32 v0, v48, v0
	v_add_f32_e32 v0, v32, v0
	v_add_f32_e32 v0, v24, v0
	v_add_f32_e32 v28, v12, v0
	v_sub_f32_e32 v0, v60, v108
	v_mul_f32_e32 v0, 0x3e0293ee, v0
	v_exp_f32_e32 v16, v0
	v_sub_f32_e32 v0, v52, v108
	v_mul_f32_e32 v0, 0x3e0293ee, v0
	v_exp_f32_e32 v8, v0
	v_sub_f32_e32 v0, v36, v108
	v_mul_f32_e32 v0, 0x3e0293ee, v0
	v_exp_f32_e32 v4, v0
	v_sub_f32_e32 v0, v20, v108
	v_mul_f32_e32 v0, 0x3e0293ee, v0
	v_exp_f32_e32 v0, v0
	v_add_f32_e32 v20, v16, v28
	v_max3_f32 v36, v41, s86, v25
	v_add_f32_e32 v20, v8, v20
	v_max3_f32 v36, v36, v9, v1
	v_add_f32_e32 v20, v4, v20
	v_max3_f32 v36, v36, v49, v33
	v_add_f32_e32 v20, v0, v20
	v_max3_f32 v36, v36, v17, v5
	ds_bpermute_b32 v28, v101, v20
	v_max3_f32 v36, v36, v57, v45
	v_max3_f32 v36, v36, v29, v13
	v_max3_f32 v36, v36, v61, v53
	v_max3_f32 v36, v36, v37, v21
	ds_bpermute_b32 v44, v101, v36
	s_waitcnt lgkmcnt(1)
	v_add_f32_e32 v20, v20, v28
	ds_bpermute_b32 v28, v105, v20
	s_waitcnt lgkmcnt(1)
	v_max_f32_e32 v44, v44, v44
	v_max_f32_e32 v36, v36, v44
	s_waitcnt lgkmcnt(0)
	v_add_f32_e32 v20, v20, v28
	ds_bpermute_b32 v44, v105, v36
	ds_bpermute_b32 v28, v106, v20
	s_waitcnt lgkmcnt(1)
	v_max_f32_e32 v44, v44, v44
	s_waitcnt lgkmcnt(0)
	v_add_f32_e32 v20, v20, v28
	v_max_f32_e32 v36, v36, v44
	ds_bpermute_b32 v28, v107, v20
	ds_bpermute_b32 v44, v106, v36
	s_waitcnt lgkmcnt(1)
	v_add_f32_e32 v108, v20, v28
	s_waitcnt lgkmcnt(0)
	v_max_f32_e32 v20, v44, v44
	v_max_f32_e32 v20, v36, v20
	ds_bpermute_b32 v28, v107, v20
	v_div_scale_f32 v109, s[10:11], v108, v108, 1.0
	v_rcp_f32_e32 v110, v109
	s_waitcnt lgkmcnt(0)
	v_max_f32_e32 v28, v28, v28
	v_max_f32_e32 v111, v20, v28
	v_sub_f32_e32 v20, v41, v111
	v_mul_f32_e32 v20, 0x3e0293ee, v20
	v_sub_f32_e32 v9, v9, v111
	v_exp_f32_e32 v60, v20
	v_sub_f32_e32 v20, v25, v111
	v_mul_f32_e32 v9, 0x3e0293ee, v9
	v_mul_f32_e32 v20, 0x3e0293ee, v20
	v_exp_f32_e32 v52, v9
	v_sub_f32_e32 v9, v49, v111
	v_exp_f32_e32 v56, v20
	v_sub_f32_e32 v1, v1, v111
	v_mul_f32_e32 v9, 0x3e0293ee, v9
	v_sub_f32_e32 v5, v5, v111
	v_mul_f32_e32 v1, 0x3e0293ee, v1
	v_exp_f32_e32 v49, v9
	v_sub_f32_e32 v9, v33, v111
	v_mul_f32_e32 v5, 0x3e0293ee, v5
	v_exp_f32_e32 v44, v1
	v_mul_f32_e32 v9, 0x3e0293ee, v9
	v_exp_f32_e32 v28, v5
	v_sub_f32_e32 v5, v57, v111
	v_add_f32_e32 v1, 0, v60
	v_exp_f32_e32 v41, v9
	v_sub_f32_e32 v9, v17, v111
	v_mul_f32_e32 v5, 0x3e0293ee, v5
	v_fma_f32 v36, -v109, v110, 1.0
	v_add_f32_e32 v1, v56, v1
	v_mul_f32_e32 v9, 0x3e0293ee, v9
	v_exp_f32_e32 v33, v5
	v_sub_f32_e32 v5, v45, v111
	v_fmac_f32_e32 v110, v36, v110
	v_add_f32_e32 v1, v52, v1
	v_exp_f32_e32 v36, v9
	v_mul_f32_e32 v5, 0x3e0293ee, v5
	v_add_f32_e32 v1, v44, v1
	v_exp_f32_e32 v25, v5
	v_sub_f32_e32 v5, v29, v111
	v_add_f32_e32 v1, v49, v1
	v_mul_f32_e32 v5, 0x3e0293ee, v5
	v_add_f32_e32 v1, v41, v1
	v_exp_f32_e32 v20, v5
	v_sub_f32_e32 v5, v13, v111
	v_add_f32_e32 v1, v36, v1
	v_mul_f32_e32 v5, 0x3e0293ee, v5
	v_add_f32_e32 v1, v28, v1
	v_exp_f32_e32 v13, v5
	v_add_f32_e32 v1, v33, v1
	v_add_f32_e32 v1, v25, v1
	v_add_f32_e32 v1, v20, v1
	v_add_f32_e32 v29, v13, v1
	v_sub_f32_e32 v1, v61, v111
	v_mul_f32_e32 v1, 0x3e0293ee, v1
	v_exp_f32_e32 v17, v1
	v_sub_f32_e32 v1, v53, v111
	v_mul_f32_e32 v1, 0x3e0293ee, v1
	v_exp_f32_e32 v9, v1
	v_sub_f32_e32 v1, v37, v111
	v_max3_f32 v37, v42, s86, v26
	v_max3_f32 v37, v37, v10, v2
	v_mul_f32_e32 v1, 0x3e0293ee, v1
	v_max3_f32 v37, v37, v50, v34
	v_exp_f32_e32 v5, v1
	v_sub_f32_e32 v1, v21, v111
	v_max3_f32 v37, v37, v18, v6
	v_mul_f32_e32 v1, 0x3e0293ee, v1
	v_max3_f32 v37, v37, v58, v46
	v_exp_f32_e32 v1, v1
	v_max3_f32 v37, v37, v30, v14
	v_add_f32_e32 v21, v17, v29
	v_max3_f32 v37, v37, v62, v54
	v_add_f32_e32 v21, v9, v21
	v_max3_f32 v37, v37, v38, v22
	v_add_f32_e32 v21, v5, v21
	ds_bpermute_b32 v45, v101, v37
	v_add_f32_e32 v21, v1, v21
	ds_bpermute_b32 v29, v101, v21
	v_div_scale_f32 v53, vcc, 1.0, v108, 1.0
	s_waitcnt lgkmcnt(1)
; DI float fexp2(float x) { return __builtin_amdgcn_exp2f(x); }
; DI float grp16_sum(float v) { v += __shfl_xor(v, 1); v += __shfl_xor(v, 2); v += __shfl_xor(v, 4); v += __shfl_xor(v, 8); return v; }
; DI float grp16_max(float v) { v = fmaxf(v, __shfl_xor(v, 1)); v = fmaxf(v, __shfl_xor(v, 2)); v = fmaxf(v, __shfl_xor(v, 4)); v = fmaxf(v, __shfl_xor(v, 8)); return v; }
; DI void mem_attn_phase(const Params& P, LAS unsigned char* lds, int r, int layer, const bf16* QKV, int nin, int qoff, bf16* CAT) {
;     ...
;         float inv[4];
; #pragma unroll
;         for (int i = 0; i < 4; ++i) { float mx = -INFINITY;
; #pragma unroll
;             for (int t = 0; t < 16; ++t) mx = fmaxf(mx, sacc[t][i]);
;             mx = grp16_max(mx); float sm = 0.f;
; #pragma unroll
;             for (int t = 0; t < 16; ++t) { const float e = fexp2((sacc[t][i] - mx) * (QK_SCALE * LOG2E)); sacc[t][i] = e; sm += e; }
;             inv[i] = 1.0f / grp16_sum(sm); }
	v_max_f32_e32 v45, v45, v45
	v_max_f32_e32 v37, v37, v45
	s_waitcnt lgkmcnt(0)
	v_add_f32_e32 v21, v21, v29
	ds_bpermute_b32 v45, v105, v37
	ds_bpermute_b32 v29, v105, v21
	v_mul_f32_e32 v57, v53, v110
	v_fma_f32 v61, -v109, v57, v53
	v_fmac_f32_e32 v57, v61, v110
	s_waitcnt lgkmcnt(1)
	v_max_f32_e32 v45, v45, v45
	s_waitcnt lgkmcnt(0)
	v_add_f32_e32 v21, v21, v29
	v_max_f32_e32 v37, v37, v45
	ds_bpermute_b32 v29, v106, v21
	ds_bpermute_b32 v45, v106, v37
	v_fma_f32 v53, -v109, v57, v53
	s_waitcnt lgkmcnt(1)
	v_add_f32_e32 v29, v21, v29
	s_waitcnt lgkmcnt(0)
	v_max_f32_e32 v21, v45, v45
	v_max_f32_e32 v37, v37, v21
	ds_bpermute_b32 v61, v107, v29
	ds_bpermute_b32 v45, v107, v37
	v_div_fmas_f32 v21, v53, v110, v57
	v_div_fixup_f32 v21, v21, v108, 1.0
	v_mul_f32_e32 v0, v0, v21
	s_waitcnt lgkmcnt(1)
	v_add_f32_e32 v110, v29, v61
	s_waitcnt lgkmcnt(0)
	v_max_f32_e32 v29, v45, v45
	v_max_f32_e32 v111, v37, v29
	v_sub_f32_e32 v6, v6, v111
	v_sub_f32_e32 v29, v42, v111
	v_mul_f32_e32 v6, 0x3e0293ee, v6
	v_mul_f32_e32 v29, 0x3e0293ee, v29
	v_sub_f32_e32 v26, v26, v111
	v_sub_f32_e32 v10, v10, v111
	v_exp_f32_e32 v42, v6
	v_sub_f32_e32 v6, v58, v111
	v_exp_f32_e32 v109, v29
	v_mul_f32_e32 v26, 0x3e0293ee, v26
	v_mul_f32_e32 v10, 0x3e0293ee, v10
	v_mul_f32_e32 v6, 0x3e0293ee, v6
	v_exp_f32_e32 v108, v26
	v_exp_f32_e32 v61, v10
	v_sub_f32_e32 v2, v2, v111
	v_sub_f32_e32 v10, v34, v111
	v_exp_f32_e32 v34, v6
	v_sub_f32_e32 v6, v46, v111
	v_mul_f32_e32 v2, 0x3e0293ee, v2
	v_mul_f32_e32 v6, 0x3e0293ee, v6
	v_exp_f32_e32 v57, v2
	v_sub_f32_e32 v2, v50, v111
	v_exp_f32_e32 v37, v6
	v_sub_f32_e32 v6, v30, v111
	v_add_f32_e32 v29, 0, v109
	v_mul_f32_e32 v2, 0x3e0293ee, v2
	v_mul_f32_e32 v6, 0x3e0293ee, v6
	v_exp_f32_e32 v50, v2
	v_add_f32_e32 v2, v108, v29
	v_exp_f32_e32 v29, v6
	v_sub_f32_e32 v6, v14, v111
	v_mul_f32_e32 v6, 0x3e0293ee, v6
	v_exp_f32_e32 v26, v6
	v_sub_f32_e32 v6, v62, v111
	v_mul_f32_e32 v6, 0x3e0293ee, v6
	v_exp_f32_e32 v14, v6
	v_sub_f32_e32 v6, v54, v111
	v_mul_f32_e32 v10, 0x3e0293ee, v10
	v_mul_f32_e32 v6, 0x3e0293ee, v6
	v_exp_f32_e32 v53, v10
	v_sub_f32_e32 v10, v18, v111
	v_exp_f32_e32 v18, v6
	v_sub_f32_e32 v6, v38, v111
	v_mul_f32_e32 v10, 0x3e0293ee, v10
	v_mul_f32_e32 v6, 0x3e0293ee, v6
	v_exp_f32_e32 v45, v10
	v_exp_f32_e32 v10, v6
	v_sub_f32_e32 v6, v22, v111
	v_max3_f32 v22, v43, s86, v27
	v_max3_f32 v22, v22, v11, v3
	v_max3_f32 v22, v22, v51, v35
	v_max3_f32 v22, v22, v19, v7
	v_max3_f32 v22, v22, v59, v47
	v_max3_f32 v22, v22, v31, v15
	v_max3_f32 v22, v22, v63, v55
	v_max3_f32 v22, v22, v39, v23
	ds_bpermute_b32 v30, v101, v22
	v_add_f32_e32 v2, v61, v2
	v_add_f32_e32 v2, v57, v2
	v_add_f32_e32 v2, v50, v2
	v_add_f32_e32 v2, v53, v2
	s_waitcnt lgkmcnt(0)
	v_max_f32_e32 v30, v30, v30
	v_max_f32_e32 v22, v22, v30
	ds_bpermute_b32 v30, v105, v22
	v_add_f32_e32 v2, v45, v2
	v_add_f32_e32 v2, v42, v2
	v_add_f32_e32 v2, v34, v2
	v_add_f32_e32 v2, v37, v2
	s_waitcnt lgkmcnt(0)
	v_max_f32_e32 v30, v30, v30
	v_max_f32_e32 v22, v22, v30
	ds_bpermute_b32 v30, v106, v22
	v_div_scale_f32 v112, s[10:11], v110, v110, 1.0
	v_add_f32_e32 v2, v29, v2
	v_mul_f32_e32 v6, 0x3e0293ee, v6
	s_waitcnt lgkmcnt(0)
	v_max_f32_e32 v30, v30, v30
	v_max_f32_e32 v22, v22, v30
	ds_bpermute_b32 v30, v107, v22
	v_rcp_f32_e32 v113, v112
	v_add_f32_e32 v2, v26, v2
	v_exp_f32_e32 v6, v6
	v_add_f32_e32 v2, v14, v2
	s_waitcnt lgkmcnt(0)
	v_max_f32_e32 v30, v30, v30
	v_max_f32_e32 v22, v22, v30
	v_sub_f32_e32 v30, v43, v22
	v_mul_f32_e32 v30, 0x3e0293ee, v30
	v_sub_f32_e32 v27, v27, v22
	v_add_f32_e32 v2, v18, v2
	v_exp_f32_e32 v30, v30
	v_mul_f32_e32 v27, 0x3e0293ee, v27
	v_sub_f32_e32 v11, v11, v22
	v_add_f32_e32 v2, v10, v2
	v_exp_f32_e32 v27, v27
	v_mul_f32_e32 v11, 0x3e0293ee, v11
	v_sub_f32_e32 v3, v3, v22
	v_add_f32_e32 v2, v6, v2
	v_fma_f32 v46, -v112, v113, 1.0
	v_exp_f32_e32 v11, v11
	v_mul_f32_e32 v3, 0x3e0293ee, v3
	v_sub_f32_e32 v51, v51, v22
	ds_bpermute_b32 v38, v101, v2
	v_fmac_f32_e32 v113, v46, v113
	v_div_scale_f32 v46, vcc, 1.0, v110, 1.0
	v_exp_f32_e32 v3, v3
	v_mul_f32_e32 v51, 0x3e0293ee, v51
	v_sub_f32_e32 v35, v35, v22
	v_mul_f32_e32 v54, v46, v113
	v_add_f32_e32 v43, 0, v30
	v_exp_f32_e32 v51, v51
	v_mul_f32_e32 v35, 0x3e0293ee, v35
	v_sub_f32_e32 v19, v19, v22
	v_fma_f32 v58, -v112, v54, v46
	v_add_f32_e32 v43, v27, v43
	v_exp_f32_e32 v35, v35
	v_mul_f32_e32 v19, 0x3e0293ee, v19
	v_sub_f32_e32 v7, v7, v22
	v_fmac_f32_e32 v54, v58, v113
	v_add_f32_e32 v43, v11, v43
	v_exp_f32_e32 v19, v19
	v_mul_f32_e32 v7, 0x3e0293ee, v7
	v_sub_f32_e32 v58, v59, v22
	v_add_f32_e32 v43, v3, v43
	v_exp_f32_e32 v7, v7
	v_mul_f32_e32 v58, 0x3e0293ee, v58
	v_sub_f32_e32 v47, v47, v22
	s_waitcnt lgkmcnt(0)
	v_add_f32_e32 v2, v2, v38
	v_add_f32_e32 v43, v51, v43
	v_exp_f32_e32 v58, v58
	v_mul_f32_e32 v47, 0x3e0293ee, v47
	v_sub_f32_e32 v31, v31, v22
	ds_bpermute_b32 v38, v105, v2
	v_add_f32_e32 v43, v35, v43
	v_exp_f32_e32 v47, v47
	v_mul_f32_e32 v31, 0x3e0293ee, v31
	v_sub_f32_e32 v15, v15, v22
	v_add_f32_e32 v43, v19, v43
	v_exp_f32_e32 v31, v31
	v_mul_f32_e32 v15, 0x3e0293ee, v15
	v_sub_f32_e32 v59, v63, v22
	v_add_f32_e32 v43, v7, v43
	v_exp_f32_e32 v15, v15
	v_mul_f32_e32 v59, 0x3e0293ee, v59
	v_sub_f32_e32 v55, v55, v22
	v_add_f32_e32 v43, v58, v43
	v_exp_f32_e32 v59, v59
	v_mul_f32_e32 v55, 0x3e0293ee, v55
	v_sub_f32_e32 v39, v39, v22
	v_add_f32_e32 v43, v47, v43
	v_exp_f32_e32 v55, v55
	v_mul_f32_e32 v39, 0x3e0293ee, v39
	v_sub_f32_e32 v22, v23, v22
	s_waitcnt lgkmcnt(0)
	v_add_f32_e32 v2, v2, v38
	v_add_f32_e32 v43, v31, v43
	v_exp_f32_e32 v39, v39
	v_mul_f32_e32 v22, 0x3e0293ee, v22
	ds_bpermute_b32 v38, v106, v2
	v_add_f32_e32 v43, v15, v43
	v_exp_f32_e32 v22, v22
	v_add_f32_e32 v23, v59, v43
	v_add_f32_e32 v23, v55, v23
	v_add_f32_e32 v23, v39, v23
	v_add_f32_e32 v23, v22, v23
	s_waitcnt lgkmcnt(0)
; #define LAS __attribute__((address_space(3)))
; DI unsigned short f2bf(float f) { return (unsigned short)(pg8::cvt_pk_bf16(f, f) & 0xffffu); }
; DI float fexp2(float x) { return __builtin_amdgcn_exp2f(x); }
; DI float grp16_sum(float v) { v += __shfl_xor(v, 1); v += __shfl_xor(v, 2); v += __shfl_xor(v, 4); v += __shfl_xor(v, 8); return v; }
; DI float grp16_max(float v) { v = fmaxf(v, __shfl_xor(v, 1)); v = fmaxf(v, __shfl_xor(v, 2)); v = fmaxf(v, __shfl_xor(v, 4)); v = fmaxf(v, __shfl_xor(v, 8)); return v; }
; DI void mem_attn_phase(const Params& P, LAS unsigned char* lds, int r, int layer, const bf16* QKV, int nin, int qoff, bf16* CAT) {
;     ...
;             mx = grp16_max(mx); float sm = 0.f;
; #pragma unroll
;             for (int t = 0; t < 16; ++t) { const float e = fexp2((sacc[t][i] - mx) * (QK_SCALE * LOG2E)); sacc[t][i] = e; sm += e; }
;             inv[i] = 1.0f / grp16_sum(sm); }
;         __syncthreads();
; #pragma unroll
;         for (int t = 0; t < 16; ++t)
; #pragma unroll
;             for (int i = 0; i < 4; ++i) ((LAS unsigned short*)(KI + (wave * 16 + 4 * g + i) * PPITCH))[16 * t + li] = f2bf(sacc[t][i] * inv[i]);
	v_add_f32_e32 v2, v2, v38
	ds_bpermute_b32 v43, v101, v23
	ds_bpermute_b32 v38, v107, v2
	v_fma_f32 v46, -v112, v54, v46
	v_div_fmas_f32 v46, v46, v113, v54
	v_div_fixup_f32 v46, v46, v110, 1.0
	s_waitcnt lgkmcnt(1)
	v_add_f32_e32 v23, v23, v43
	s_waitcnt lgkmcnt(0)
	v_add_f32_e32 v2, v2, v38
	ds_bpermute_b32 v38, v105, v23
	v_div_scale_f32 v43, s[10:11], v2, v2, 1.0
	v_rcp_f32_e32 v54, v43
	s_waitcnt lgkmcnt(0)
	v_add_f32_e32 v23, v23, v38
	ds_bpermute_b32 v38, v106, v23
	v_fma_f32 v62, -v43, v54, 1.0
	v_fmac_f32_e32 v54, v62, v54
	v_div_scale_f32 v62, vcc, 1.0, v2, 1.0
	s_waitcnt lgkmcnt(0)
	v_add_f32_e32 v23, v23, v38
	ds_bpermute_b32 v38, v107, v23
	v_mul_f32_e32 v63, v62, v54
	v_fma_f32 v101, -v43, v63, v62
	v_fmac_f32_e32 v63, v101, v54
	v_fma_f32 v43, -v43, v63, v62
	s_waitcnt lgkmcnt(0)
	v_add_f32_e32 v23, v23, v38
	v_div_scale_f32 v38, s[10:11], v23, v23, 1.0
	v_rcp_f32_e32 v62, v38
	v_div_fmas_f32 v43, v43, v54, v63
	v_div_fixup_f32 v43, v43, v2, 1.0
	v_fma_f32 v2, -v38, v62, 1.0
	v_fmac_f32_e32 v62, v2, v62
	v_div_scale_f32 v2, vcc, 1.0, v23, 1.0
	v_mul_f32_e32 v54, v2, v62
	v_fma_f32 v63, -v38, v54, v2
	v_fmac_f32_e32 v54, v63, v62
	v_fma_f32 v2, -v38, v54, v2
	v_div_fmas_f32 v2, v2, v62, v54
	v_div_fixup_f32 v23, v2, v23, 1.0
	v_lshlrev_b32_e32 v2, 2, v81
	v_add_u32_e32 v38, s7, v2
	v_lshlrev_b32_e32 v54, 1, v80
	v_mul_lo_u32 v38, v38, s15
	v_mul_f32_e32 v62, v104, v21
	v_add3_u32 v38, 0, v54, v38
	v_mul_f32_e32 v54, v60, v46
	v_cvt_pk_bf16_f32 v62, v62, v62
	ds_write_b16 v38, v62
	v_cvt_pk_bf16_f32 v54, v54, v54
	ds_write_b16 v38, v54 offset:528
	v_mul_f32_e32 v54, v109, v43
	v_mul_f32_e32 v30, v30, v23
	v_cvt_pk_bf16_f32 v54, v54, v54
	ds_write_b16 v38, v54 offset:1056
	v_cvt_pk_bf16_f32 v30, v30, v30
	ds_write_b16 v38, v30 offset:1584
	v_mul_f32_e32 v30, v103, v21
	v_cvt_pk_bf16_f32 v30, v30, v30
	ds_write_b16 v38, v30 offset:32
	v_mul_f32_e32 v30, v56, v46
	v_cvt_pk_bf16_f32 v30, v30, v30
	ds_write_b16 v38, v30 offset:560
	v_mul_f32_e32 v30, v108, v43
	v_mul_f32_e32 v27, v27, v23
	v_cvt_pk_bf16_f32 v30, v30, v30
	ds_write_b16 v38, v30 offset:1088
	v_cvt_pk_bf16_f32 v27, v27, v27
	ds_write_b16 v38, v27 offset:1616
	v_mul_f32_e32 v27, v102, v21
	v_cvt_pk_bf16_f32 v27, v27, v27
	ds_write_b16 v38, v27 offset:64
	v_mul_f32_e32 v27, v52, v46
	v_cvt_pk_bf16_f32 v27, v27, v27
	ds_write_b16 v38, v27 offset:592
	v_mul_f32_e32 v27, v61, v43
	v_mul_f32_e32 v11, v11, v23
	v_cvt_pk_bf16_f32 v27, v27, v27
	ds_write_b16 v38, v27 offset:1120
	v_cvt_pk_bf16_f32 v11, v11, v11
	ds_write_b16 v38, v11 offset:1648
	v_mul_f32_e32 v11, v99, v21
	v_cvt_pk_bf16_f32 v11, v11, v11
	ds_write_b16 v38, v11 offset:96
	v_mul_f32_e32 v11, v44, v46
	v_cvt_pk_bf16_f32 v11, v11, v11
	ds_write_b16 v38, v11 offset:624
	v_mul_f32_e32 v11, v57, v43
	v_mul_f32_e32 v3, v3, v23
	v_cvt_pk_bf16_f32 v11, v11, v11
	ds_write_b16 v38, v11 offset:1152
	v_cvt_pk_bf16_f32 v3, v3, v3
	ds_write_b16 v38, v3 offset:1680
	v_mul_f32_e32 v3, v100, v21
	v_cvt_pk_bf16_f32 v3, v3, v3
	ds_write_b16 v38, v3 offset:128
	v_mul_f32_e32 v3, v49, v46
	v_cvt_pk_bf16_f32 v3, v3, v3
	ds_write_b16 v38, v3 offset:656
	v_mul_f32_e32 v3, v50, v43
	v_cvt_pk_bf16_f32 v3, v3, v3
	ds_write_b16 v38, v3 offset:1184
	v_mul_f32_e32 v3, v51, v23
	v_cvt_pk_bf16_f32 v3, v3, v3
	ds_write_b16 v38, v3 offset:1712
	v_mul_f32_e32 v3, v98, v21
	v_cvt_pk_bf16_f32 v3, v3, v3
	ds_write_b16 v38, v3 offset:160
	v_mul_f32_e32 v3, v41, v46
	v_cvt_pk_bf16_f32 v3, v3, v3
	ds_write_b16 v38, v3 offset:688
	v_mul_f32_e32 v3, v53, v43
	v_cvt_pk_bf16_f32 v3, v3, v3
	ds_write_b16 v38, v3 offset:1216
	v_mul_f32_e32 v3, v35, v23
	v_cvt_pk_bf16_f32 v3, v3, v3
	ds_write_b16 v38, v3 offset:1744
	v_mul_f32_e32 v3, v97, v21
	v_cvt_pk_bf16_f32 v3, v3, v3
	ds_write_b16 v38, v3 offset:192
	v_mul_f32_e32 v3, v36, v46
	v_cvt_pk_bf16_f32 v3, v3, v3
	ds_write_b16 v38, v3 offset:720
	v_mul_f32_e32 v3, v45, v43
	v_cvt_pk_bf16_f32 v3, v3, v3
	ds_write_b16 v38, v3 offset:1248
	v_mul_f32_e32 v3, v19, v23
	v_cvt_pk_bf16_f32 v3, v3, v3
	ds_write_b16 v38, v3 offset:1776
	v_mul_f32_e32 v3, v40, v21
	v_cvt_pk_bf16_f32 v3, v3, v3
	ds_write_b16 v38, v3 offset:224
	v_mul_f32_e32 v3, v28, v46
	v_cvt_pk_bf16_f32 v3, v3, v3
	ds_write_b16 v38, v3 offset:752
	v_mul_f32_e32 v3, v42, v43
	v_cvt_pk_bf16_f32 v3, v3, v3
	ds_write_b16 v38, v3 offset:1280
	v_mul_f32_e32 v3, v7, v23
	v_cvt_pk_bf16_f32 v3, v3, v3
	ds_write_b16 v38, v3 offset:1808
	v_mul_f32_e32 v3, v48, v21
	v_cvt_pk_bf16_f32 v3, v3, v3
	ds_write_b16 v38, v3 offset:256
	v_mul_f32_e32 v3, v33, v46
	v_cvt_pk_bf16_f32 v3, v3, v3
	ds_write_b16 v38, v3 offset:784
	v_mul_f32_e32 v3, v34, v43
	v_cvt_pk_bf16_f32 v3, v3, v3
	ds_write_b16 v38, v3 offset:1312
	v_mul_f32_e32 v3, v58, v23
	v_cvt_pk_bf16_f32 v3, v3, v3
	ds_write_b16 v38, v3 offset:1840
	v_mul_f32_e32 v3, v32, v21
	v_cvt_pk_bf16_f32 v3, v3, v3
	ds_write_b16 v38, v3 offset:288
	v_mul_f32_e32 v3, v25, v46
	v_cvt_pk_bf16_f32 v3, v3, v3
	ds_write_b16 v38, v3 offset:816
	v_mul_f32_e32 v3, v37, v43
	v_cvt_pk_bf16_f32 v3, v3, v3
	ds_write_b16 v38, v3 offset:1344
	v_mul_f32_e32 v3, v47, v23
	v_cvt_pk_bf16_f32 v3, v3, v3
	ds_write_b16 v38, v3 offset:1872
	v_mul_f32_e32 v3, v24, v21
	v_cvt_pk_bf16_f32 v3, v3, v3
	ds_write_b16 v38, v3 offset:320
	v_mul_f32_e32 v3, v20, v46
	v_cvt_pk_bf16_f32 v3, v3, v3
	ds_write_b16 v38, v3 offset:848
	v_mul_f32_e32 v3, v29, v43
	v_cvt_pk_bf16_f32 v3, v3, v3
	ds_write_b16 v38, v3 offset:1376
	v_mul_f32_e32 v3, v31, v23
	v_cvt_pk_bf16_f32 v3, v3, v3
	ds_write_b16 v38, v3 offset:1904
	v_mul_f32_e32 v3, v12, v21
	v_cvt_pk_bf16_f32 v3, v3, v3
	ds_write_b16 v38, v3 offset:352
	v_mul_f32_e32 v3, v13, v46
	v_cvt_pk_bf16_f32 v3, v3, v3
; #define LAS __attribute__((address_space(3)))
; DI unsigned short f2bf(float f) { return (unsigned short)(pg8::cvt_pk_bf16(f, f) & 0xffffu); }
; DI f32x4 mfma16(bf16x8 a, bf16x8 b, f32x4 c) { return __builtin_amdgcn_mfma_f32_16x16x32_bf16(a, b, c, 0, 0, 0); }
; DI void mem_attn_phase(const Params& P, LAS unsigned char* lds, int r, int layer, const bf16* QKV, int nin, int qoff, bf16* CAT) {
;     ...
; #pragma unroll
;         for (int t = 0; t < 16; ++t)
; #pragma unroll
;             for (int i = 0; i < 4; ++i) ((LAS unsigned short*)(KI + (wave * 16 + 4 * g + i) * PPITCH))[16 * t + li] = f2bf(sacc[t][i] * inv[i]);
;         __syncthreads();
;         f32x4 oacc[8];
; #pragma unroll
;         for (int t = 0; t < 8; ++t) oacc[t] = (f32x4){0.f, 0.f, 0.f, 0.f};
; #pragma unroll
;         for (int ks = 0; ks < 8; ++ks) { const bf16x8 pa = frag_row(KI, PPITCH, wave * 16, 32 * ks, lane);
; #pragma unroll
;             for (int th = 0; th < 2; ++th) { bf16x8 vf[4];
; #pragma unroll
;                 for (int t = 0; t < 4; ++t) vf[t] = frag_tr(VI, PITCH, 32 * ks, 16 * (4 * th + t), lane);
;                 __builtin_amdgcn_sched_barrier(0);
; #pragma unroll
;                 for (int t = 0; t < 4; ++t) oacc[4 * th + t] = mfma16(pa, vf[t], oacc[4 * th + t]);
;                 __builtin_amdgcn_sched_barrier(0); } }
	ds_write_b16 v38, v3 offset:880
	v_mul_f32_e32 v3, v26, v43
	v_cvt_pk_bf16_f32 v3, v3, v3
	ds_write_b16 v38, v3 offset:1408
	v_mul_f32_e32 v3, v15, v23
	v_cvt_pk_bf16_f32 v3, v3, v3
	ds_write_b16 v38, v3 offset:1936
	v_mul_f32_e32 v3, v16, v21
	v_cvt_pk_bf16_f32 v3, v3, v3
	ds_write_b16 v38, v3 offset:384
	v_mul_f32_e32 v3, v17, v46
	v_cvt_pk_bf16_f32 v3, v3, v3
	ds_write_b16 v38, v3 offset:912
	v_mul_f32_e32 v3, v14, v43
	v_cvt_pk_bf16_f32 v3, v3, v3
	ds_write_b16 v38, v3 offset:1440
	v_mul_f32_e32 v3, v59, v23
	v_cvt_pk_bf16_f32 v3, v3, v3
	ds_write_b16 v38, v3 offset:1968
	v_mul_f32_e32 v3, v8, v21
	v_cvt_pk_bf16_f32 v3, v3, v3
	ds_write_b16 v38, v3 offset:416
	v_mul_f32_e32 v3, v9, v46
	v_cvt_pk_bf16_f32 v3, v3, v3
	ds_write_b16 v38, v3 offset:944
	v_mul_f32_e32 v3, v18, v43
	v_cvt_pk_bf16_f32 v3, v3, v3
	ds_write_b16 v38, v3 offset:1472
	v_mul_f32_e32 v3, v55, v23
	v_cvt_pk_bf16_f32 v3, v3, v3
	ds_write_b16 v38, v3 offset:2000
	v_mul_f32_e32 v3, v4, v21
	v_cvt_pk_bf16_f32 v3, v3, v3
	ds_write_b16 v38, v3 offset:448
	v_mul_f32_e32 v3, v5, v46
	v_cvt_pk_bf16_f32 v3, v3, v3
	ds_write_b16 v38, v3 offset:976
	v_mul_f32_e32 v3, v10, v43
	v_cvt_pk_bf16_f32 v3, v3, v3
	ds_write_b16 v38, v3 offset:1504
	v_mul_f32_e32 v3, v39, v23
	v_cvt_pk_bf16_f32 v3, v3, v3
	ds_write_b16 v38, v3 offset:2032
	v_cvt_pk_bf16_f32 v0, v0, v0
	ds_write_b16 v38, v0 offset:480
	v_mul_f32_e32 v0, v1, v46
	v_cvt_pk_bf16_f32 v0, v0, v0
	ds_write_b16 v38, v0 offset:1008
	v_mul_f32_e32 v0, v6, v43
	v_cvt_pk_bf16_f32 v0, v0, v0
	ds_write_b16 v38, v0 offset:1536
	v_mul_f32_e32 v0, v22, v23
	v_cvt_pk_bf16_f32 v0, v0, v0
	ds_write_b16 v38, v0 offset:2064
	s_waitcnt lgkmcnt(0)
	s_barrier
	ds_read_b128 v[4:7], v96
	ds_read_b64_tr_b16 v[8:9], v95
	ds_read_b64_tr_b16 v[12:13], v95 offset:32
	ds_read_b64_tr_b16 v[16:17], v95 offset:64
	ds_read_b64_tr_b16 v[20:21], v95 offset:96
	ds_read_b64_tr_b16 v[10:11], v95 offset:1088
	ds_read_b64_tr_b16 v[14:15], v95 offset:1120
	ds_read_b64_tr_b16 v[18:19], v95 offset:1152
	ds_read_b64_tr_b16 v[22:23], v95 offset:1184
	s_waitcnt lgkmcnt(3)
	v_mfma_f32_16x16x32_bf16 v[8:11], v[4:7], v[8:11], 0
	s_waitcnt lgkmcnt(2)
	v_mfma_f32_16x16x32_bf16 v[12:15], v[4:7], v[12:15], 0
	s_waitcnt lgkmcnt(1)
	v_mfma_f32_16x16x32_bf16 v[16:19], v[4:7], v[16:19], 0
	s_waitcnt lgkmcnt(0)
	v_mfma_f32_16x16x32_bf16 v[20:23], v[4:7], v[20:23], 0
	ds_read_b64_tr_b16 v[24:25], v95 offset:128
	ds_read_b64_tr_b16 v[28:29], v95 offset:160
	ds_read_b64_tr_b16 v[32:33], v95 offset:192
	ds_read_b64_tr_b16 v[36:37], v95 offset:224
	ds_read_b64_tr_b16 v[26:27], v95 offset:1216
	ds_read_b64_tr_b16 v[30:31], v95 offset:1248
	ds_read_b64_tr_b16 v[34:35], v95 offset:1280
	ds_read_b64_tr_b16 v[38:39], v95 offset:1312
	s_waitcnt lgkmcnt(3)
	v_mfma_f32_16x16x32_bf16 v[24:27], v[4:7], v[24:27], 0
	s_waitcnt lgkmcnt(2)
	v_mfma_f32_16x16x32_bf16 v[28:31], v[4:7], v[28:31], 0
	s_waitcnt lgkmcnt(1)
	v_mfma_f32_16x16x32_bf16 v[32:35], v[4:7], v[32:35], 0
	s_waitcnt lgkmcnt(0)
	v_mfma_f32_16x16x32_bf16 v[4:7], v[4:7], v[36:39], 0
	ds_read_b128 v[36:39], v96 offset:64
	ds_read_b64_tr_b16 v[40:41], v95 offset:8704
	ds_read_b64_tr_b16 v[44:45], v95 offset:8736
	ds_read_b64_tr_b16 v[48:49], v95 offset:8768
	ds_read_b64_tr_b16 v[52:53], v95 offset:8800
	ds_read_b64_tr_b16 v[42:43], v95 offset:9792
	ds_read_b64_tr_b16 v[46:47], v95 offset:9824
	ds_read_b64_tr_b16 v[50:51], v95 offset:9856
	ds_read_b64_tr_b16 v[54:55], v95 offset:9888
	s_waitcnt lgkmcnt(3)
	v_mfma_f32_16x16x32_bf16 v[8:11], v[36:39], v[40:43], v[8:11]
	s_waitcnt lgkmcnt(2)
	v_mfma_f32_16x16x32_bf16 v[12:15], v[36:39], v[44:47], v[12:15]
	s_waitcnt lgkmcnt(1)
	v_mfma_f32_16x16x32_bf16 v[16:19], v[36:39], v[48:51], v[16:19]
	s_waitcnt lgkmcnt(0)
	v_mfma_f32_16x16x32_bf16 v[20:23], v[36:39], v[52:55], v[20:23]
	ds_read_b64_tr_b16 v[40:41], v95 offset:8832
	ds_read_b64_tr_b16 v[44:45], v95 offset:8864
	ds_read_b64_tr_b16 v[48:49], v95 offset:8896
	ds_read_b64_tr_b16 v[52:53], v95 offset:8928
	ds_read_b64_tr_b16 v[42:43], v95 offset:9920
	ds_read_b64_tr_b16 v[46:47], v95 offset:9952
	ds_read_b64_tr_b16 v[50:51], v95 offset:9984
	ds_read_b64_tr_b16 v[54:55], v95 offset:10016
	s_waitcnt lgkmcnt(3)
	v_mfma_f32_16x16x32_bf16 v[24:27], v[36:39], v[40:43], v[24:27]
	s_waitcnt lgkmcnt(2)
	v_mfma_f32_16x16x32_bf16 v[28:31], v[36:39], v[44:47], v[28:31]
	s_waitcnt lgkmcnt(1)
	v_mfma_f32_16x16x32_bf16 v[32:35], v[36:39], v[48:51], v[32:35]
	s_waitcnt lgkmcnt(0)
	v_mfma_f32_16x16x32_bf16 v[4:7], v[36:39], v[52:55], v[4:7]
	ds_read_b128 v[36:39], v96 offset:128
	ds_read_b64_tr_b16 v[40:41], v95 offset:17408
	ds_read_b64_tr_b16 v[44:45], v95 offset:17440
	ds_read_b64_tr_b16 v[48:49], v95 offset:17472
	ds_read_b64_tr_b16 v[52:53], v95 offset:17504
	ds_read_b64_tr_b16 v[42:43], v95 offset:18496
	ds_read_b64_tr_b16 v[46:47], v95 offset:18528
	ds_read_b64_tr_b16 v[50:51], v95 offset:18560
	ds_read_b64_tr_b16 v[54:55], v95 offset:18592
	s_waitcnt lgkmcnt(3)
	v_mfma_f32_16x16x32_bf16 v[8:11], v[36:39], v[40:43], v[8:11]
	s_waitcnt lgkmcnt(2)
	v_mfma_f32_16x16x32_bf16 v[12:15], v[36:39], v[44:47], v[12:15]
	s_waitcnt lgkmcnt(1)
	v_mfma_f32_16x16x32_bf16 v[16:19], v[36:39], v[48:51], v[16:19]
	s_waitcnt lgkmcnt(0)
	v_mfma_f32_16x16x32_bf16 v[20:23], v[36:39], v[52:55], v[20:23]
	ds_read_b64_tr_b16 v[40:41], v95 offset:17536
	ds_read_b64_tr_b16 v[44:45], v95 offset:17568
	ds_read_b64_tr_b16 v[48:49], v95 offset:17600
	ds_read_b64_tr_b16 v[52:53], v95 offset:17632
	ds_read_b64_tr_b16 v[42:43], v95 offset:18624
	ds_read_b64_tr_b16 v[46:47], v95 offset:18656
	ds_read_b64_tr_b16 v[50:51], v95 offset:18688
	ds_read_b64_tr_b16 v[54:55], v95 offset:18720
	s_waitcnt lgkmcnt(3)
; DI f32x4 mfma16(bf16x8 a, bf16x8 b, f32x4 c) { return __builtin_amdgcn_mfma_f32_16x16x32_bf16(a, b, c, 0, 0, 0); }
; DI void mem_attn_phase(const Params& P, LAS unsigned char* lds, int r, int layer, const bf16* QKV, int nin, int qoff, bf16* CAT) {
;     ...
; #pragma unroll
;         for (int ks = 0; ks < 8; ++ks) { const bf16x8 pa = frag_row(KI, PPITCH, wave * 16, 32 * ks, lane);
; #pragma unroll
;             for (int th = 0; th < 2; ++th) { bf16x8 vf[4];
; #pragma unroll
;                 for (int t = 0; t < 4; ++t) vf[t] = frag_tr(VI, PITCH, 32 * ks, 16 * (4 * th + t), lane);
;                 __builtin_amdgcn_sched_barrier(0);
; #pragma unroll
;                 for (int t = 0; t < 4; ++t) oacc[4 * th + t] = mfma16(pa, vf[t], oacc[4 * th + t]);
;                 __builtin_amdgcn_sched_barrier(0); } }
	v_mfma_f32_16x16x32_bf16 v[24:27], v[36:39], v[40:43], v[24:27]
	s_waitcnt lgkmcnt(2)
	v_mfma_f32_16x16x32_bf16 v[28:31], v[36:39], v[44:47], v[28:31]
	s_waitcnt lgkmcnt(1)
	v_mfma_f32_16x16x32_bf16 v[32:35], v[36:39], v[48:51], v[32:35]
	s_waitcnt lgkmcnt(0)
	v_mfma_f32_16x16x32_bf16 v[4:7], v[36:39], v[52:55], v[4:7]
	ds_read_b128 v[36:39], v96 offset:192
	ds_read_b64_tr_b16 v[40:41], v95 offset:26112
	ds_read_b64_tr_b16 v[44:45], v95 offset:26144
	ds_read_b64_tr_b16 v[48:49], v95 offset:26176
	ds_read_b64_tr_b16 v[52:53], v95 offset:26208
	ds_read_b64_tr_b16 v[42:43], v95 offset:27200
	ds_read_b64_tr_b16 v[46:47], v95 offset:27232
	ds_read_b64_tr_b16 v[50:51], v95 offset:27264
	ds_read_b64_tr_b16 v[54:55], v95 offset:27296
	s_waitcnt lgkmcnt(3)
	v_mfma_f32_16x16x32_bf16 v[8:11], v[36:39], v[40:43], v[8:11]
	s_waitcnt lgkmcnt(2)
	v_mfma_f32_16x16x32_bf16 v[12:15], v[36:39], v[44:47], v[12:15]
	s_waitcnt lgkmcnt(1)
	v_mfma_f32_16x16x32_bf16 v[16:19], v[36:39], v[48:51], v[16:19]
	s_waitcnt lgkmcnt(0)
	v_mfma_f32_16x16x32_bf16 v[20:23], v[36:39], v[52:55], v[20:23]
	ds_read_b64_tr_b16 v[40:41], v95 offset:26240
	ds_read_b64_tr_b16 v[44:45], v95 offset:26272
	ds_read_b64_tr_b16 v[48:49], v95 offset:26304
	ds_read_b64_tr_b16 v[52:53], v95 offset:26336
	ds_read_b64_tr_b16 v[42:43], v95 offset:27328
	ds_read_b64_tr_b16 v[46:47], v95 offset:27360
	ds_read_b64_tr_b16 v[50:51], v95 offset:27392
	ds_read_b64_tr_b16 v[54:55], v95 offset:27424
	s_waitcnt lgkmcnt(3)
	v_mfma_f32_16x16x32_bf16 v[24:27], v[36:39], v[40:43], v[24:27]
	s_waitcnt lgkmcnt(2)
	v_mfma_f32_16x16x32_bf16 v[28:31], v[36:39], v[44:47], v[28:31]
	s_waitcnt lgkmcnt(1)
	v_mfma_f32_16x16x32_bf16 v[32:35], v[36:39], v[48:51], v[32:35]
	s_waitcnt lgkmcnt(0)
	v_mfma_f32_16x16x32_bf16 v[4:7], v[36:39], v[52:55], v[4:7]
	ds_read_b128 v[36:39], v96 offset:256
	ds_read_b64_tr_b16 v[40:41], v95 offset:34816
	ds_read_b64_tr_b16 v[44:45], v95 offset:34848
	ds_read_b64_tr_b16 v[48:49], v95 offset:34880
	ds_read_b64_tr_b16 v[52:53], v95 offset:34912
	ds_read_b64_tr_b16 v[42:43], v95 offset:35904
	ds_read_b64_tr_b16 v[46:47], v95 offset:35936
	ds_read_b64_tr_b16 v[50:51], v95 offset:35968
	ds_read_b64_tr_b16 v[54:55], v95 offset:36000
	s_waitcnt lgkmcnt(3)
	v_mfma_f32_16x16x32_bf16 v[8:11], v[36:39], v[40:43], v[8:11]
	s_waitcnt lgkmcnt(2)
	v_mfma_f32_16x16x32_bf16 v[12:15], v[36:39], v[44:47], v[12:15]
	s_waitcnt lgkmcnt(1)
	v_mfma_f32_16x16x32_bf16 v[16:19], v[36:39], v[48:51], v[16:19]
	s_waitcnt lgkmcnt(0)
	v_mfma_f32_16x16x32_bf16 v[20:23], v[36:39], v[52:55], v[20:23]
	ds_read_b64_tr_b16 v[40:41], v95 offset:34944
	ds_read_b64_tr_b16 v[44:45], v95 offset:34976
	ds_read_b64_tr_b16 v[48:49], v95 offset:35008
	ds_read_b64_tr_b16 v[52:53], v95 offset:35040
	ds_read_b64_tr_b16 v[42:43], v95 offset:36032
	ds_read_b64_tr_b16 v[46:47], v95 offset:36064
	ds_read_b64_tr_b16 v[50:51], v95 offset:36096
	ds_read_b64_tr_b16 v[54:55], v95 offset:36128
	s_waitcnt lgkmcnt(3)
	v_mfma_f32_16x16x32_bf16 v[24:27], v[36:39], v[40:43], v[24:27]
	s_waitcnt lgkmcnt(2)
	v_mfma_f32_16x16x32_bf16 v[28:31], v[36:39], v[44:47], v[28:31]
	s_waitcnt lgkmcnt(1)
	v_mfma_f32_16x16x32_bf16 v[32:35], v[36:39], v[48:51], v[32:35]
	s_waitcnt lgkmcnt(0)
	v_mfma_f32_16x16x32_bf16 v[4:7], v[36:39], v[52:55], v[4:7]
	ds_read_b128 v[36:39], v96 offset:320
	ds_read_b64_tr_b16 v[40:41], v95 offset:43520
	ds_read_b64_tr_b16 v[44:45], v95 offset:43552
	ds_read_b64_tr_b16 v[48:49], v95 offset:43584
	ds_read_b64_tr_b16 v[52:53], v95 offset:43616
	ds_read_b64_tr_b16 v[42:43], v95 offset:44608
	ds_read_b64_tr_b16 v[46:47], v95 offset:44640
	ds_read_b64_tr_b16 v[50:51], v95 offset:44672
	ds_read_b64_tr_b16 v[54:55], v95 offset:44704
	s_waitcnt lgkmcnt(3)
	v_mfma_f32_16x16x32_bf16 v[8:11], v[36:39], v[40:43], v[8:11]
	s_waitcnt lgkmcnt(2)
	v_mfma_f32_16x16x32_bf16 v[12:15], v[36:39], v[44:47], v[12:15]
	s_waitcnt lgkmcnt(1)
	v_mfma_f32_16x16x32_bf16 v[16:19], v[36:39], v[48:51], v[16:19]
	s_waitcnt lgkmcnt(0)
	v_mfma_f32_16x16x32_bf16 v[20:23], v[36:39], v[52:55], v[20:23]
	ds_read_b64_tr_b16 v[40:41], v95 offset:43648
	ds_read_b64_tr_b16 v[44:45], v95 offset:43680
	ds_read_b64_tr_b16 v[48:49], v95 offset:43712
	ds_read_b64_tr_b16 v[52:53], v95 offset:43744
	ds_read_b64_tr_b16 v[42:43], v95 offset:44736
	ds_read_b64_tr_b16 v[46:47], v95 offset:44768
	ds_read_b64_tr_b16 v[50:51], v95 offset:44800
	ds_read_b64_tr_b16 v[54:55], v95 offset:44832
	s_waitcnt lgkmcnt(3)
	v_mfma_f32_16x16x32_bf16 v[24:27], v[36:39], v[40:43], v[24:27]
	s_waitcnt lgkmcnt(2)
	v_mfma_f32_16x16x32_bf16 v[28:31], v[36:39], v[44:47], v[28:31]
	s_waitcnt lgkmcnt(1)
	v_mfma_f32_16x16x32_bf16 v[32:35], v[36:39], v[48:51], v[32:35]
	s_waitcnt lgkmcnt(0)
	v_mfma_f32_16x16x32_bf16 v[4:7], v[36:39], v[52:55], v[4:7]
	ds_read_b128 v[36:39], v96 offset:384
	ds_read_b64_tr_b16 v[40:41], v95 offset:52224
	ds_read_b64_tr_b16 v[44:45], v95 offset:52256
	ds_read_b64_tr_b16 v[48:49], v95 offset:52288
	ds_read_b64_tr_b16 v[52:53], v95 offset:52320
	ds_read_b64_tr_b16 v[42:43], v95 offset:53312
	ds_read_b64_tr_b16 v[46:47], v95 offset:53344
	ds_read_b64_tr_b16 v[50:51], v95 offset:53376
	ds_read_b64_tr_b16 v[54:55], v95 offset:53408
	s_waitcnt lgkmcnt(3)
	v_mfma_f32_16x16x32_bf16 v[8:11], v[36:39], v[40:43], v[8:11]
	s_waitcnt lgkmcnt(2)
	v_mfma_f32_16x16x32_bf16 v[12:15], v[36:39], v[44:47], v[12:15]
	s_waitcnt lgkmcnt(1)
	v_mfma_f32_16x16x32_bf16 v[16:19], v[36:39], v[48:51], v[16:19]
	s_waitcnt lgkmcnt(0)
; DI f32x4 mfma16(bf16x8 a, bf16x8 b, f32x4 c) { return __builtin_amdgcn_mfma_f32_16x16x32_bf16(a, b, c, 0, 0, 0); }
; DI void mem_attn_phase(const Params& P, LAS unsigned char* lds, int r, int layer, const bf16* QKV, int nin, int qoff, bf16* CAT) {
;     ...
; #pragma unroll
;         for (int ks = 0; ks < 8; ++ks) { const bf16x8 pa = frag_row(KI, PPITCH, wave * 16, 32 * ks, lane);
; #pragma unroll
;             for (int th = 0; th < 2; ++th) { bf16x8 vf[4];
; #pragma unroll
;                 for (int t = 0; t < 4; ++t) vf[t] = frag_tr(VI, PITCH, 32 * ks, 16 * (4 * th + t), lane);
;                 __builtin_amdgcn_sched_barrier(0);
; #pragma unroll
;                 for (int t = 0; t < 4; ++t) oacc[4 * th + t] = mfma16(pa, vf[t], oacc[4 * th + t]);
;                 __builtin_amdgcn_sched_barrier(0); } }
	v_mfma_f32_16x16x32_bf16 v[20:23], v[36:39], v[52:55], v[20:23]
	ds_read_b64_tr_b16 v[40:41], v95 offset:52352
	ds_read_b64_tr_b16 v[44:45], v95 offset:52384
	ds_read_b64_tr_b16 v[48:49], v95 offset:52416
	ds_read_b64_tr_b16 v[52:53], v95 offset:52448
	ds_read_b64_tr_b16 v[42:43], v95 offset:53440
	ds_read_b64_tr_b16 v[46:47], v95 offset:53472
	ds_read_b64_tr_b16 v[50:51], v95 offset:53504
	ds_read_b64_tr_b16 v[54:55], v95 offset:53536
	s_waitcnt lgkmcnt(3)
	v_mfma_f32_16x16x32_bf16 v[24:27], v[36:39], v[40:43], v[24:27]
	s_waitcnt lgkmcnt(2)
	v_mfma_f32_16x16x32_bf16 v[28:31], v[36:39], v[44:47], v[28:31]
	s_waitcnt lgkmcnt(1)
	v_mfma_f32_16x16x32_bf16 v[32:35], v[36:39], v[48:51], v[32:35]
	s_waitcnt lgkmcnt(0)
	v_mfma_f32_16x16x32_bf16 v[4:7], v[36:39], v[52:55], v[4:7]
	ds_read_b128 v[36:39], v96 offset:448
	ds_read_b64_tr_b16 v[40:41], v95 offset:60928
	ds_read_b64_tr_b16 v[44:45], v95 offset:60960
	ds_read_b64_tr_b16 v[48:49], v95 offset:60992
	ds_read_b64_tr_b16 v[52:53], v95 offset:61024
	ds_read_b64_tr_b16 v[42:43], v95 offset:62016
	ds_read_b64_tr_b16 v[46:47], v95 offset:62048
	ds_read_b64_tr_b16 v[50:51], v95 offset:62080
	ds_read_b64_tr_b16 v[54:55], v95 offset:62112
	s_waitcnt lgkmcnt(3)
	v_mfma_f32_16x16x32_bf16 v[8:11], v[36:39], v[40:43], v[8:11]
	s_waitcnt lgkmcnt(2)
	v_mfma_f32_16x16x32_bf16 v[12:15], v[36:39], v[44:47], v[12:15]
	s_waitcnt lgkmcnt(1)
	v_mfma_f32_16x16x32_bf16 v[16:19], v[36:39], v[48:51], v[16:19]
	s_waitcnt lgkmcnt(0)
	v_mfma_f32_16x16x32_bf16 v[20:23], v[36:39], v[52:55], v[20:23]
	ds_read_b64_tr_b16 v[40:41], v95 offset:61056
	ds_read_b64_tr_b16 v[44:45], v95 offset:61088
	ds_read_b64_tr_b16 v[48:49], v95 offset:61120
	ds_read_b64_tr_b16 v[52:53], v95 offset:61152
	ds_read_b64_tr_b16 v[42:43], v95 offset:62144
	ds_read_b64_tr_b16 v[46:47], v95 offset:62176
	ds_read_b64_tr_b16 v[50:51], v95 offset:62208
	ds_read_b64_tr_b16 v[54:55], v95 offset:62240
	s_waitcnt lgkmcnt(3)
	v_mfma_f32_16x16x32_bf16 v[24:27], v[36:39], v[40:43], v[24:27]
	s_waitcnt lgkmcnt(2)
	v_mfma_f32_16x16x32_bf16 v[28:31], v[36:39], v[44:47], v[28:31]
	s_waitcnt lgkmcnt(1)
	v_mfma_f32_16x16x32_bf16 v[32:35], v[36:39], v[48:51], v[32:35]
	s_waitcnt lgkmcnt(0)
; DI unsigned short f2bf(float f) { return (unsigned short)(pg8::cvt_pk_bf16(f, f) & 0xffffu); }
; DI void mem_attn_phase(const Params& P, LAS unsigned char* lds, int r, int layer, const bf16* QKV, int nin, int qoff, bf16* CAT) {
;     ...
; #pragma unroll
;         for (int t = 0; t < 8; ++t)
; #pragma unroll
;             for (int i = 0; i < 4; ++i) CAT[(size_t)(row0 + 4 * g + i) * D + 1536 + h * 128 + 16 * t + li] = f2bf(oacc[t][i]);
;         __syncthreads();
	v_mfma_f32_16x16x32_bf16 v[4:7], v[36:39], v[52:55], v[4:7]
	s_add_u32 s10, s16, s62
	s_addc_u32 s11, s17, 0
	s_mov_b32 vcc_lo, 0x55555555
	s_mov_b32 vcc_hi, 0x55555555
	v_add_u32_e32 v232, s9, v2
	v_mbcnt_lo_u32_b32 v233, -1, 0
	v_mbcnt_hi_u32_b32 v233, -1, v233
	v_mov_b32_e32 v235, 0
	v_and_b32_e32 v233, 1, v233
	v_mul_u32_u24_e32 v233, 30, v233
	v_lshl_add_u32 v233, v80, 1, v233
	v_mov_b32_e32 v234, v232
	v_lshlrev_b32_e32 v234, 12, v234
	v_add_u32_e32 v234, v234, v233
	v_lshl_add_u64 v[216:217], s[10:11], 0, v[234:235]
	v_or_b32_e32 v234, 1, v232
	v_lshlrev_b32_e32 v234, 12, v234
	v_add_u32_e32 v234, v234, v233
	v_lshl_add_u64 v[218:219], s[10:11], 0, v[234:235]
	v_or_b32_e32 v234, 2, v232
	v_lshlrev_b32_e32 v234, 12, v234
	v_add_u32_e32 v234, v234, v233
	v_lshl_add_u64 v[220:221], s[10:11], 0, v[234:235]
	v_or_b32_e32 v234, 3, v232
	v_lshlrev_b32_e32 v234, 12, v234
	v_add_u32_e32 v234, v234, v233
	v_lshl_add_u64 v[222:223], s[10:11], 0, v[234:235]
	v_mov_b32_dpp v224, v8 quad_perm:[1,0,3,2] row_mask:0xf bank_mask:0xf
	v_mov_b32_dpp v225, v12 quad_perm:[1,0,3,2] row_mask:0xf bank_mask:0xf
	v_cndmask_b32_e32 v226, v225, v8, vcc
	v_cndmask_b32_e32 v227, v12, v224, vcc
	v_cvt_pk_bf16_f32 v228, v226, v227
	global_store_dword v[216:217], v228, off offset:3072
	v_mov_b32_dpp v224, v9 quad_perm:[1,0,3,2] row_mask:0xf bank_mask:0xf
	v_mov_b32_dpp v225, v13 quad_perm:[1,0,3,2] row_mask:0xf bank_mask:0xf
	v_cndmask_b32_e32 v226, v225, v9, vcc
	v_cndmask_b32_e32 v227, v13, v224, vcc
	v_cvt_pk_bf16_f32 v229, v226, v227
	global_store_dword v[218:219], v229, off offset:3072
	v_mov_b32_dpp v224, v10 quad_perm:[1,0,3,2] row_mask:0xf bank_mask:0xf
	v_mov_b32_dpp v225, v14 quad_perm:[1,0,3,2] row_mask:0xf bank_mask:0xf
	v_cndmask_b32_e32 v226, v225, v10, vcc
	v_cndmask_b32_e32 v227, v14, v224, vcc
	v_cvt_pk_bf16_f32 v230, v226, v227
	global_store_dword v[220:221], v230, off offset:3072
	v_mov_b32_dpp v224, v11 quad_perm:[1,0,3,2] row_mask:0xf bank_mask:0xf
	v_mov_b32_dpp v225, v15 quad_perm:[1,0,3,2] row_mask:0xf bank_mask:0xf
	v_cndmask_b32_e32 v226, v225, v11, vcc
	v_cndmask_b32_e32 v227, v15, v224, vcc
	v_cvt_pk_bf16_f32 v231, v226, v227
	global_store_dword v[222:223], v231, off offset:3072
	v_mov_b32_dpp v224, v16 quad_perm:[1,0,3,2] row_mask:0xf bank_mask:0xf
	v_mov_b32_dpp v225, v20 quad_perm:[1,0,3,2] row_mask:0xf bank_mask:0xf
	v_cndmask_b32_e32 v226, v225, v16, vcc
	v_cndmask_b32_e32 v227, v20, v224, vcc
	v_cvt_pk_bf16_f32 v228, v226, v227
	global_store_dword v[216:217], v228, off offset:3136
	v_mov_b32_dpp v224, v17 quad_perm:[1,0,3,2] row_mask:0xf bank_mask:0xf
	v_mov_b32_dpp v225, v21 quad_perm:[1,0,3,2] row_mask:0xf bank_mask:0xf
	v_cndmask_b32_e32 v226, v225, v17, vcc
	v_cndmask_b32_e32 v227, v21, v224, vcc
	v_cvt_pk_bf16_f32 v229, v226, v227
	global_store_dword v[218:219], v229, off offset:3136
	v_mov_b32_dpp v224, v18 quad_perm:[1,0,3,2] row_mask:0xf bank_mask:0xf
	v_mov_b32_dpp v225, v22 quad_perm:[1,0,3,2] row_mask:0xf bank_mask:0xf
	v_cndmask_b32_e32 v226, v225, v18, vcc
	v_cndmask_b32_e32 v227, v22, v224, vcc
	v_cvt_pk_bf16_f32 v230, v226, v227
	global_store_dword v[220:221], v230, off offset:3136
	v_mov_b32_dpp v224, v19 quad_perm:[1,0,3,2] row_mask:0xf bank_mask:0xf
	v_mov_b32_dpp v225, v23 quad_perm:[1,0,3,2] row_mask:0xf bank_mask:0xf
	v_cndmask_b32_e32 v226, v225, v19, vcc
	v_cndmask_b32_e32 v227, v23, v224, vcc
	v_cvt_pk_bf16_f32 v231, v226, v227
	global_store_dword v[222:223], v231, off offset:3136
	v_mov_b32_dpp v224, v24 quad_perm:[1,0,3,2] row_mask:0xf bank_mask:0xf
	v_mov_b32_dpp v225, v28 quad_perm:[1,0,3,2] row_mask:0xf bank_mask:0xf
	v_cndmask_b32_e32 v226, v225, v24, vcc
	v_cndmask_b32_e32 v227, v28, v224, vcc
	v_cvt_pk_bf16_f32 v228, v226, v227
	global_store_dword v[216:217], v228, off offset:3200
	v_mov_b32_dpp v224, v25 quad_perm:[1,0,3,2] row_mask:0xf bank_mask:0xf
	v_mov_b32_dpp v225, v29 quad_perm:[1,0,3,2] row_mask:0xf bank_mask:0xf
	v_cndmask_b32_e32 v226, v225, v25, vcc
	v_cndmask_b32_e32 v227, v29, v224, vcc
	v_cvt_pk_bf16_f32 v229, v226, v227
	global_store_dword v[218:219], v229, off offset:3200
	v_mov_b32_dpp v224, v26 quad_perm:[1,0,3,2] row_mask:0xf bank_mask:0xf
	v_mov_b32_dpp v225, v30 quad_perm:[1,0,3,2] row_mask:0xf bank_mask:0xf
	v_cndmask_b32_e32 v226, v225, v26, vcc
	v_cndmask_b32_e32 v227, v30, v224, vcc
	v_cvt_pk_bf16_f32 v230, v226, v227
	global_store_dword v[220:221], v230, off offset:3200
	v_mov_b32_dpp v224, v27 quad_perm:[1,0,3,2] row_mask:0xf bank_mask:0xf
	v_mov_b32_dpp v225, v31 quad_perm:[1,0,3,2] row_mask:0xf bank_mask:0xf
	v_cndmask_b32_e32 v226, v225, v27, vcc
	v_cndmask_b32_e32 v227, v31, v224, vcc
	v_cvt_pk_bf16_f32 v231, v226, v227
	global_store_dword v[222:223], v231, off offset:3200
	v_mov_b32_dpp v224, v32 quad_perm:[1,0,3,2] row_mask:0xf bank_mask:0xf
	v_mov_b32_dpp v225, v4 quad_perm:[1,0,3,2] row_mask:0xf bank_mask:0xf
	v_cndmask_b32_e32 v226, v225, v32, vcc
	v_cndmask_b32_e32 v227, v4, v224, vcc
	v_cvt_pk_bf16_f32 v228, v226, v227
	global_store_dword v[216:217], v228, off offset:3264
	v_mov_b32_dpp v224, v33 quad_perm:[1,0,3,2] row_mask:0xf bank_mask:0xf
	v_mov_b32_dpp v225, v5 quad_perm:[1,0,3,2] row_mask:0xf bank_mask:0xf
	v_cndmask_b32_e32 v226, v225, v33, vcc
	v_cndmask_b32_e32 v227, v5, v224, vcc
	v_cvt_pk_bf16_f32 v229, v226, v227
	global_store_dword v[218:219], v229, off offset:3264
	v_mov_b32_dpp v224, v34 quad_perm:[1,0,3,2] row_mask:0xf bank_mask:0xf
	v_mov_b32_dpp v225, v6 quad_perm:[1,0,3,2] row_mask:0xf bank_mask:0xf
	v_cndmask_b32_e32 v226, v225, v34, vcc
	v_cndmask_b32_e32 v227, v6, v224, vcc
	v_cvt_pk_bf16_f32 v230, v226, v227
	global_store_dword v[220:221], v230, off offset:3264
	v_mov_b32_dpp v224, v35 quad_perm:[1,0,3,2] row_mask:0xf bank_mask:0xf
	v_mov_b32_dpp v225, v7 quad_perm:[1,0,3,2] row_mask:0xf bank_mask:0xf
	v_cndmask_b32_e32 v226, v225, v35, vcc
	v_cndmask_b32_e32 v227, v7, v224, vcc
	v_cvt_pk_bf16_f32 v231, v226, v227
	global_store_dword v[222:223], v231, off offset:3264
	s_mov_b32 s9, s42
	s_waitcnt lgkmcnt(0)
	s_barrier
	s_add_i32 s0, s9, s0
	s_cmpk_lt_i32 s0, 0x200
	s_cbranch_scc1 .LBB0_220
